# EpiOutFin row groups 2 and 7: the four xin loads issued together
# speedup vs baseline: 1.0003x; 1.0003x over previous
;     __device__ __forceinline__ void fused(f32x4 (&acc)[2][2][4][2], const Unit& u, int wr, int wc, int fr, int fq, PG8_LAS unsigned char* lds, int wid, int lane) const {
;     ...
;             for (int m = 0; m < 4; ++m) { const size_t ro = (size_t)(row0 + ai * HALF + m * 16) * 1024 + col0; float s = 0.f;
; #pragma unroll
;                 for (int bj = 0; bj < 2; ++bj)
; #pragma unroll
;                     for (int n = 0; n < 2; ++n) { const f32x4 xi = __builtin_nontemporal_load((const f32x4*)(xin + ro + bj * HALF + 16 * n));
;                         const f32x4 v = xi + gt[bj][n] * acc[ai][bj][m][n]; acc[ai][bj][m][n] = v;
;                         s += (v[0] * v[0] + v[1] * v[1]) + (v[2] * v[2] + v[3] * v[3]); }
;                 s += __shfl_xor(s, 16); s += __shfl_xor(s, 32);
;                 if (fq == 0) P[(ai * HALF + wr * 64 + m * 16 + fr) * 4 + wc] = s; }
.LBB0_673:
	s_or_b64 exec, exec, s[30:31]
	v_or_b32_e32 v116, 32, v164
	s_waitcnt lgkmcnt(0)
	v_ashrrev_i32_e32 v117, 31, v116
	v_lshlrev_b64 v[116:117], 12, v[116:117]
	v_lshl_add_u64 v[156:157], s[18:19], 0, v[116:117]
	v_lshl_add_u64 v[162:163], v[160:161], 2, v[156:157]
	global_load_dwordx4 v[156:159], v[162:163], off nt
	global_load_dwordx4 v[174:177], v[162:163], off offset:64 nt
	global_load_dwordx4 v[212:215], v[162:163], off offset:512 nt
	global_load_dwordx4 v[216:219], v[162:163], off offset:576 nt
	s_waitcnt vmcnt(3)
	v_pk_fma_f32 v[114:115], v[114:115], v[102:103], v[158:159]
	s_waitcnt vmcnt(2)
	v_pk_fma_f32 v[110:111], v[110:111], v[94:95], v[176:177]
	v_pk_fma_f32 v[108:109], v[108:109], v[92:93], v[174:175]
	v_pk_fma_f32 v[156:157], v[112:113], v[100:101], v[156:157]
	v_mul_f32_e32 v113, v115, v115
	v_mul_f32_e32 v112, v157, v157
	v_fmac_f32_e32 v112, v156, v156
	v_fmac_f32_e32 v113, v114, v114
	v_add_f32_e32 v112, v112, v113
	v_mul_f32_e32 v113, v109, v109
	v_mul_f32_e32 v158, v111, v111
	v_fmac_f32_e32 v113, v108, v108
	v_fmac_f32_e32 v158, v110, v110
	v_add_f32_e32 v113, v113, v158
	v_add_f32_e32 v112, v112, v113
	s_waitcnt vmcnt(1)
	v_pk_fma_f32 v[106:107], v[106:107], v[86:87], v[214:215]
	v_pk_fma_f32 v[104:105], v[104:105], v[84:85], v[212:213]
	v_mul_f32_e32 v113, v105, v105
	v_mul_f32_e32 v158, v107, v107
	v_fmac_f32_e32 v113, v104, v104
	v_fmac_f32_e32 v158, v106, v106
	v_add_f32_e32 v113, v113, v158
	v_add_f32_e32 v158, v112, v113
	s_waitcnt vmcnt(0)
	v_pk_fma_f32 v[98:99], v[98:99], v[78:79], v[218:219]
	v_pk_fma_f32 v[112:113], v[96:97], v[76:77], v[216:217]
	v_mul_f32_e32 v97, v99, v99
	v_mul_f32_e32 v96, v113, v113
	v_fmac_f32_e32 v96, v112, v112
	v_fmac_f32_e32 v97, v98, v98
	v_add_f32_e32 v96, v96, v97
	v_add_f32_e32 v96, v158, v96
	ds_bpermute_b32 v97, v170, v96
	s_waitcnt lgkmcnt(0)
	v_add_f32_e32 v96, v96, v97
	ds_bpermute_b32 v97, v171, v96
	s_and_saveexec_b64 s[30:31], vcc
	s_cbranch_execz .LBB0_675
	s_waitcnt lgkmcnt(0)
	v_add_f32_e32 v96, v96, v97
	ds_write_b32 v172, v96 offset:512

;     __device__ __forceinline__ void fused(f32x4 (&acc)[2][2][4][2], const Unit& u, int wr, int wc, int fr, int fq, PG8_LAS unsigned char* lds, int wid, int lane) const {
;     ...
;             for (int m = 0; m < 4; ++m) { const size_t ro = (size_t)(row0 + ai * HALF + m * 16) * 1024 + col0; float s = 0.f;
; #pragma unroll
;                 for (int bj = 0; bj < 2; ++bj)
; #pragma unroll
;                     for (int n = 0; n < 2; ++n) { const f32x4 xi = __builtin_nontemporal_load((const f32x4*)(xin + ro + bj * HALF + 16 * n));
;                         const f32x4 v = xi + gt[bj][n] * acc[ai][bj][m][n]; acc[ai][bj][m][n] = v;
;                         s += (v[0] * v[0] + v[1] * v[1]) + (v[2] * v[2] + v[3] * v[3]); }
;                 s += __shfl_xor(s, 16); s += __shfl_xor(s, 32);
;                 if (fq == 0) P[(ai * HALF + wr * 64 + m * 16 + fr) * 4 + wc] = s; }
.LBB0_683:
	s_or_b64 exec, exec, s[30:31]
	s_mov_b64 s[30:31], 0xb0000
	v_lshl_add_u64 v[166:167], v[166:167], 0, s[30:31]
	s_waitcnt lgkmcnt(0)
	v_lshl_add_u64 v[174:175], s[18:19], 0, v[166:167]
	v_lshl_add_u64 v[160:161], v[160:161], 2, v[174:175]
	global_load_dwordx4 v[174:177], v[160:161], off nt
	global_load_dwordx4 v[212:215], v[160:161], off offset:64 nt
	global_load_dwordx4 v[216:219], v[160:161], off offset:512 nt
	global_load_dwordx4 v[220:223], v[160:161], off offset:576 nt
	s_waitcnt vmcnt(3)
	v_pk_fma_f32 v[102:103], v[18:19], v[102:103], v[176:177]
	v_pk_fma_f32 v[100:101], v[16:17], v[100:101], v[174:175]
	v_mul_f32_e32 v17, v103, v103
	v_mul_f32_e32 v16, v101, v101
	v_fmac_f32_e32 v16, v100, v100
	v_fmac_f32_e32 v17, v102, v102
	v_add_f32_e32 v173, v16, v17
	s_waitcnt vmcnt(2)
	v_pk_fma_f32 v[94:95], v[14:15], v[94:95], v[214:215]
	v_pk_fma_f32 v[92:93], v[12:13], v[92:93], v[212:213]
	v_mul_f32_e32 v13, v95, v95
	v_mul_f32_e32 v12, v93, v93
	v_fmac_f32_e32 v12, v92, v92
	v_fmac_f32_e32 v13, v94, v94
	v_add_f32_e32 v12, v12, v13
	v_add_f32_e32 v16, v173, v12
	s_waitcnt vmcnt(1)
	v_pk_fma_f32 v[86:87], v[10:11], v[86:87], v[218:219]
	v_pk_fma_f32 v[84:85], v[8:9], v[84:85], v[216:217]
	v_mul_f32_e32 v9, v87, v87
	v_mul_f32_e32 v8, v85, v85
	v_fmac_f32_e32 v8, v84, v84
	v_fmac_f32_e32 v9, v86, v86
	v_add_f32_e32 v8, v8, v9
	v_add_f32_e32 v12, v16, v8
	s_waitcnt vmcnt(0)
	v_pk_fma_f32 v[78:79], v[6:7], v[78:79], v[222:223]
	v_pk_fma_f32 v[76:77], v[4:5], v[76:77], v[220:221]
	v_mul_f32_e32 v5, v79, v79
	v_mul_f32_e32 v4, v77, v77
	v_fmac_f32_e32 v4, v76, v76
	v_fmac_f32_e32 v5, v78, v78
	v_add_f32_e32 v4, v4, v5
	v_add_f32_e32 v4, v12, v4
	ds_bpermute_b32 v5, v170, v4
	s_waitcnt lgkmcnt(0)
	v_add_f32_e32 v4, v4, v5
	ds_bpermute_b32 v5, v171, v4
	s_and_saveexec_b64 s[18:19], vcc
	s_cbranch_execz .LBB0_685
	s_waitcnt lgkmcnt(0)
	v_add_f32_e32 v4, v4, v5
	ds_write_b32 v172, v4 offset:2816
